# first 240 layer-1 mixer-in weight tiles converted by the idle workgroups of the layer-1 FFN1-in phase instead of after the layer-0 branch GEMM
# baseline (speedup 1.0000x reference)
.LBB0_1498:
	v_readlane_b32 s98, v254, 22
	v_readlane_b32 s8, v253, 29
	v_readlane_b32 s9, v253, 30
	s_and_b64 s[4:5], s[8:9], s[4:5]
	s_lshl_b32 s99, s98, 8
	s_or_b32 s99, s99, s56
	s_cmpk_eq_i32 s99, 0x9
	s_cselect_b32 s98, 0, 2
	s_cmpk_eq_i32 s99, 0x100
	s_cselect_b32 s99, 1, s98
	s_cmpk_lt_i32 s99, 0x2
	s_cselect_b64 s[8:9], -1, 0
	s_and_b64 s[4:5], s[4:5], s[8:9]
	s_andn2_b64 vcc, exec, s[4:5]
	v_readlane_b32 s2, v253, 46
	s_mov_b32 s26, s51
	s_cmp_eq_u32 s99, 1
	s_cselect_b32 s98, 0xf0, 0
	s_nop 0
	s_sub_i32 s2, s2, s98
	s_sub_i32 s26, s26, s98
	s_cbranch_vccz .LBB0_1562

.LBB0_1528:
	s_mul_hi_i32 s19, s14, s8
	s_mul_i32 s18, s14, s8
	s_ashr_i32 s9, s8, 31
	s_lshl_b64 s[18:19], s[18:19], 2
	v_ashrrev_i32_e32 v4, 5, v2
	s_add_u32 s16, s16, s18
	v_and_b32_e32 v5, -2, v4
	s_addc_u32 s17, s17, s19
	v_max_i32_e32 v152, 0, v22
	v_add_u32_e32 v6, 16, v5
	v_lshl_add_u64 v[0:1], v[152:153], 2, s[16:17]
	v_mad_i64_i32 v[6:7], s[16:17], s14, v6, 0
	v_lshl_add_u64 v[6:7], v[6:7], 2, v[0:1]
	global_load_dword v6, v[6:7], off
	v_add_u32_e32 v7, 17, v5
	v_mad_i64_i32 v[8:9], s[16:17], s14, v7, 0
	v_lshl_add_u64 v[8:9], v[8:9], 2, v[0:1]
	global_load_dword v7, v[8:9], off
	v_add_u32_e32 v8, 32, v5
	v_mad_i64_i32 v[8:9], s[16:17], s14, v8, 0
	v_lshl_add_u64 v[8:9], v[8:9], 2, v[0:1]
	global_load_dword v8, v[8:9], off
	v_add_u32_e32 v9, 33, v5
	v_mad_i64_i32 v[10:11], s[16:17], s14, v9, 0
	v_lshl_add_u64 v[10:11], v[10:11], 2, v[0:1]
	global_load_dword v9, v[10:11], off
	v_add_u32_e32 v10, 48, v5
	v_mad_i64_i32 v[10:11], s[16:17], s14, v10, 0
	v_lshl_add_u64 v[10:11], v[10:11], 2, v[0:1]
	global_load_dword v10, v[10:11], off
	v_add_u32_e32 v11, 49, v5
	v_mad_i64_i32 v[14:15], s[16:17], s14, v11, 0
	v_lshl_add_u64 v[14:15], v[14:15], 2, v[0:1]
	v_add_u32_e32 v12, 64, v5
	global_load_dword v11, v[14:15], off
	v_mad_i64_i32 v[14:15], s[16:17], s14, v12, 0
	v_lshl_add_u64 v[14:15], v[14:15], 2, v[0:1]
	global_load_dword v12, v[14:15], off
	v_add_u32_e32 v14, 0x41, v5
	v_mad_i64_i32 v[14:15], s[16:17], s14, v14, 0
	v_lshl_add_u64 v[14:15], v[14:15], 2, v[0:1]
	global_load_dword v14, v[14:15], off
	v_add_u32_e32 v15, 0x50, v5
	v_mad_i64_i32 v[16:17], s[16:17], s14, v15, 0
	v_lshl_add_u64 v[16:17], v[16:17], 2, v[0:1]
	global_load_dword v15, v[16:17], off
	v_add_u32_e32 v16, 0x51, v5
	v_mad_i64_i32 v[16:17], s[16:17], s14, v16, 0
	v_lshl_add_u64 v[16:17], v[16:17], 2, v[0:1]
	global_load_dword v16, v[16:17], off
	v_add_u32_e32 v17, 0x60, v5
	v_mad_i64_i32 v[18:19], s[16:17], s14, v17, 0
	v_lshl_add_u64 v[18:19], v[18:19], 2, v[0:1]
	global_load_dword v17, v[18:19], off
	v_add_u32_e32 v18, 0x61, v5
	v_mad_i64_i32 v[18:19], s[16:17], s14, v18, 0
	v_lshl_add_u64 v[18:19], v[18:19], 2, v[0:1]
	global_load_dword v18, v[18:19], off
	v_add_u32_e32 v19, 0x70, v5
	v_mad_i64_i32 v[20:21], s[16:17], s14, v19, 0
	v_lshl_add_u64 v[20:21], v[20:21], 2, v[0:1]
	global_load_dword v19, v[20:21], off
	v_add_u32_e32 v20, 0x71, v5
	v_mad_i64_i32 v[20:21], s[16:17], s14, v20, 0
	v_lshl_add_u64 v[20:21], v[20:21], 2, v[0:1]
	global_load_dword v20, v[20:21], off
	v_add_u32_e32 v21, 0x80, v5
	v_mad_i64_i32 v[24:25], s[16:17], s14, v21, 0
	v_lshl_add_u64 v[24:25], v[24:25], 2, v[0:1]
	v_add_u32_e32 v23, 0x81, v5
	global_load_dword v21, v[24:25], off
	v_mad_i64_i32 v[24:25], s[16:17], s14, v23, 0
	v_lshl_add_u64 v[24:25], v[24:25], 2, v[0:1]
	global_load_dword v23, v[24:25], off
	v_add_u32_e32 v24, 0x90, v5
	v_mad_i64_i32 v[24:25], s[16:17], s14, v24, 0
	v_lshl_add_u64 v[24:25], v[24:25], 2, v[0:1]
	global_load_dword v24, v[24:25], off
	v_add_u32_e32 v25, 0x91, v5
	v_mad_i64_i32 v[26:27], s[16:17], s14, v25, 0
	v_lshl_add_u64 v[26:27], v[26:27], 2, v[0:1]
	global_load_dword v25, v[26:27], off
	v_add_u32_e32 v26, 0xa0, v5
	v_mad_i64_i32 v[26:27], s[16:17], s14, v26, 0
	v_lshl_add_u64 v[26:27], v[26:27], 2, v[0:1]
	global_load_dword v28, v[26:27], off
	v_add_u32_e32 v26, 0xa1, v5
	v_mad_i64_i32 v[26:27], s[16:17], s14, v26, 0
	v_lshl_add_u64 v[26:27], v[26:27], 2, v[0:1]
	global_load_dword v29, v[26:27], off
	v_add_u32_e32 v26, 0xb0, v5
	v_mad_i64_i32 v[26:27], s[16:17], s14, v26, 0
	v_lshl_add_u64 v[26:27], v[26:27], 2, v[0:1]
	global_load_dword v30, v[26:27], off
	v_add_u32_e32 v26, 0xb1, v5
	v_mad_i64_i32 v[26:27], s[16:17], s14, v26, 0
	v_lshl_add_u64 v[26:27], v[26:27], 2, v[0:1]
	global_load_dword v31, v[26:27], off
	v_add_u32_e32 v26, 0xc0, v5
	v_mad_i64_i32 v[26:27], s[16:17], s14, v26, 0
	v_lshl_add_u64 v[26:27], v[26:27], 2, v[0:1]
	global_load_dword v32, v[26:27], off
	v_add_u32_e32 v26, 0xc1, v5
	v_mad_i64_i32 v[26:27], s[16:17], s14, v26, 0
	v_lshl_add_u64 v[26:27], v[26:27], 2, v[0:1]
	global_load_dword v33, v[26:27], off
	v_add_u32_e32 v26, 0xd0, v5
	v_mad_i64_i32 v[26:27], s[16:17], s14, v26, 0
	v_lshl_add_u64 v[26:27], v[26:27], 2, v[0:1]
	global_load_dword v34, v[26:27], off
	v_add_u32_e32 v26, 0xd1, v5
	v_mad_i64_i32 v[26:27], s[16:17], s14, v26, 0
	v_lshl_add_u64 v[26:27], v[26:27], 2, v[0:1]
	global_load_dword v35, v[26:27], off
	v_add_u32_e32 v26, 0xe0, v5
	v_mad_i64_i32 v[26:27], s[16:17], s14, v26, 0
	v_lshl_add_u64 v[26:27], v[26:27], 2, v[0:1]
	global_load_dword v36, v[26:27], off
	v_add_u32_e32 v26, 0xe1, v5
	v_mad_i64_i32 v[26:27], s[16:17], s14, v26, 0
	v_lshl_add_u64 v[26:27], v[26:27], 2, v[0:1]
	global_load_dword v37, v[26:27], off
	v_add_u32_e32 v26, 0xf0, v5
	v_mad_i64_i32 v[26:27], s[16:17], s14, v26, 0
	v_lshl_add_u64 v[26:27], v[26:27], 2, v[0:1]
	global_load_dword v38, v[26:27], off
	v_add_u32_e32 v26, 0xf1, v5
	v_mad_i64_i32 v[26:27], s[16:17], s14, v26, 0
	v_lshl_add_u64 v[26:27], v[26:27], 2, v[0:1]
	global_load_dword v39, v[26:27], off
	v_mad_i64_i32 v[26:27], s[16:17], s14, v5, 0
	v_lshl_add_u64 v[26:27], v[26:27], 2, v[0:1]
	v_cmp_gt_i32_e32 vcc, 0, v22
	global_load_dword v22, v[26:27], off
	v_or_b32_e32 v26, 1, v4
	v_mad_i64_i32 v[26:27], s[14:15], s14, v26, 0
	v_lshl_add_u64 v[0:1], v[26:27], 2, v[0:1]
	global_load_dword v0, v[0:1], off
	v_mul_u32_u24_e32 v13, 0x210, v13
	v_lshlrev_b32_e32 v1, 1, v5
	s_waitcnt vmcnt(0)
	v_cndmask_b32_e64 v5, v6, 0, vcc
	v_cndmask_b32_e64 v6, v7, 0, vcc
	v_add3_u32 v1, 0, v13, v1
	v_cvt_pk_bf16_f32 v5, v5, v6
	v_cndmask_b32_e64 v6, v11, 0, vcc
	s_lshl_b64 s[8:9], s[8:9], 1
	s_add_u32 s8, s12, s8
	s_addc_u32 s9, s13, s9
	v_cndmask_b32_e64 v22, v22, 0, vcc
	v_cndmask_b32_e64 v0, v0, 0, vcc
	v_cvt_pk_bf16_f32 v0, v22, v0
	ds_write2_b32 v1, v0, v5 offset1:8
	v_cndmask_b32_e64 v0, v8, 0, vcc
	v_cndmask_b32_e64 v5, v9, 0, vcc
	v_cvt_pk_bf16_f32 v0, v0, v5
	v_cndmask_b32_e64 v5, v10, 0, vcc
	v_cvt_pk_bf16_f32 v5, v5, v6
	ds_write2_b32 v1, v0, v5 offset0:16 offset1:24
	v_cndmask_b32_e64 v0, v12, 0, vcc
	v_cndmask_b32_e64 v5, v14, 0, vcc
	v_cvt_pk_bf16_f32 v0, v0, v5
	v_cndmask_b32_e64 v5, v15, 0, vcc
	v_cndmask_b32_e64 v6, v16, 0, vcc
	v_cvt_pk_bf16_f32 v5, v5, v6
	ds_write2_b32 v1, v0, v5 offset0:32 offset1:40
	v_cndmask_b32_e64 v0, v17, 0, vcc
	v_cndmask_b32_e64 v5, v18, 0, vcc
	v_cvt_pk_bf16_f32 v0, v0, v5
	v_cndmask_b32_e64 v5, v19, 0, vcc
	v_cndmask_b32_e64 v6, v20, 0, vcc
	v_cvt_pk_bf16_f32 v5, v5, v6
	ds_write2_b32 v1, v0, v5 offset0:48 offset1:56
	v_cndmask_b32_e64 v0, v21, 0, vcc
	v_cndmask_b32_e64 v5, v23, 0, vcc
	v_cvt_pk_bf16_f32 v0, v0, v5
	v_cndmask_b32_e64 v5, v24, 0, vcc
	v_cndmask_b32_e64 v6, v25, 0, vcc
	v_cvt_pk_bf16_f32 v5, v5, v6
	ds_write2_b32 v1, v0, v5 offset0:64 offset1:72
	v_cndmask_b32_e64 v0, v28, 0, vcc
	v_cndmask_b32_e64 v5, v29, 0, vcc
	v_cvt_pk_bf16_f32 v0, v0, v5
	v_cndmask_b32_e64 v5, v30, 0, vcc
	v_cndmask_b32_e64 v6, v31, 0, vcc
	v_cvt_pk_bf16_f32 v5, v5, v6
	ds_write2_b32 v1, v0, v5 offset0:80 offset1:88
	v_cndmask_b32_e64 v0, v32, 0, vcc
	v_cndmask_b32_e64 v5, v33, 0, vcc
	v_cvt_pk_bf16_f32 v0, v0, v5
	v_cndmask_b32_e64 v5, v34, 0, vcc
	v_cndmask_b32_e64 v6, v35, 0, vcc
	v_cvt_pk_bf16_f32 v5, v5, v6
	ds_write2_b32 v1, v0, v5 offset0:96 offset1:104
	v_cndmask_b32_e64 v0, v36, 0, vcc
	v_cndmask_b32_e64 v5, v37, 0, vcc
	v_cvt_pk_bf16_f32 v0, v0, v5
	v_cndmask_b32_e64 v5, v38, 0, vcc
	v_cndmask_b32_e64 v6, v39, 0, vcc
	v_cvt_pk_bf16_f32 v5, v5, v6
	ds_write2_b32 v1, v0, v5 offset0:112 offset1:120
	v_lshlrev_b32_e32 v0, 4, v2
	v_and_b32_e32 v152, 0x1f0, v0
	v_add_u32_e32 v0, 0, v152
	v_lshl_add_u64 v[10:11], s[8:9], 0, v[152:153]
	v_mad_u64_u32 v[6:7], s[8:9], v4, s69, v[0:1]
	s_waitcnt lgkmcnt(0)
	s_barrier
	ds_read_b128 v[6:9], v6
	v_add_u32_e32 v1, v3, v4
	v_mad_i64_i32 v[4:5], s[8:9], s10, v1, 0
	v_add_u32_e32 v1, 0x200, v2
	v_lshl_add_u64 v[4:5], v[4:5], 1, v[10:11]
	v_ashrrev_i32_e32 v1, 5, v1
	s_waitcnt lgkmcnt(0)
	global_store_dwordx4 v[4:5], v[6:9], off
	v_mad_u64_u32 v[4:5], s[8:9], v1, s69, v[0:1]
	ds_read_b128 v[4:7], v4
	v_add_u32_e32 v1, v3, v1
	v_mad_i64_i32 v[8:9], s[8:9], s10, v1, 0
	v_add_u32_e32 v1, 0x400, v2
	v_lshl_add_u64 v[8:9], v[8:9], 1, v[10:11]
	v_ashrrev_i32_e32 v1, 5, v1
	s_waitcnt lgkmcnt(0)
	global_store_dwordx4 v[8:9], v[4:7], off
	s_nop 1
	v_mad_u64_u32 v[4:5], s[8:9], v1, s69, v[0:1]
	ds_read_b128 v[4:7], v4
	v_add_u32_e32 v1, v3, v1
	v_mad_i64_i32 v[8:9], s[8:9], s10, v1, 0
	v_add_u32_e32 v1, 0x600, v2
	v_ashrrev_i32_e32 v2, 5, v1
	v_lshl_add_u64 v[8:9], v[8:9], 1, v[10:11]
	v_mad_u64_u32 v[0:1], s[8:9], v2, s69, v[0:1]
	s_waitcnt lgkmcnt(0)
	global_store_dwordx4 v[8:9], v[4:7], off
	ds_read_b128 v[4:7], v0
	v_add_u32_e32 v0, v3, v2
	v_mad_i64_i32 v[0:1], s[8:9], s10, v0, 0
	s_add_i32 s8, s2, 0x80
	v_readlane_b32 s98, v254, 22
	v_lshl_add_u64 v[0:1], v[0:1], 1, v[10:11]
	s_cmpk_lt_i32 s2, 0x190
	s_mov_b32 s2, s8
	s_waitcnt lgkmcnt(0)
	global_store_dwordx4 v[0:1], v[4:7], off
	s_barrier
	s_cbranch_scc0 .LBB0_1498

.LBB0_1561:
	v_cndmask_b32_e64 v0, v0, 0, s[8:9]
	v_cndmask_b32_e64 v1, v1, 0, s[8:9]
	v_cvt_pk_bf16_f32 v2, v4, v5
	v_cvt_pk_bf16_f32 v0, v0, v1
	s_ashr_i32 s5, s4, 31
	ds_write2_b32 v20, v2, v0 offset0:112 offset1:120
	v_lshlrev_b32_e32 v0, 4, v22
	s_lshl_b64 s[4:5], s[4:5], 1
	v_and_b32_e32 v152, 0x1f0, v0
	s_add_u32 s4, s14, s4
	v_add_u32_e32 v4, 0, v152
	s_addc_u32 s5, s15, s5
	v_lshl_add_u64 v[6:7], s[4:5], 0, v[152:153]
	v_mad_u64_u32 v[0:1], s[4:5], v25, s69, v[4:5]
	s_waitcnt lgkmcnt(0)
	s_barrier
	ds_read_b128 v[0:3], v0
	v_add_u32_e32 v5, v24, v25
	v_ashrrev_i32_e32 v8, 31, v5
	v_mul_lo_u32 v10, s12, v8
	v_mul_lo_u32 v11, s13, v5
	v_mad_u64_u32 v[8:9], s[4:5], s12, v5, 0
	v_add3_u32 v9, v9, v10, v11
	v_lshl_add_u64 v[8:9], v[8:9], 1, v[6:7]
	s_waitcnt lgkmcnt(0)
	global_store_dwordx4 v[8:9], v[0:3], off
	s_add_i32 s26, s26, 64
	s_add_i32 s2, s2, 64
	v_add_u32_e32 v0, 0x200, v22
	v_ashrrev_i32_e32 v5, 5, v0
	v_mad_u64_u32 v[0:1], s[4:5], v5, s69, v[4:5]
	ds_read_b128 v[0:3], v0
	v_add_u32_e32 v5, v24, v5
	v_ashrrev_i32_e32 v8, 31, v5
	v_mul_lo_u32 v10, s12, v8
	v_mul_lo_u32 v11, s13, v5
	v_mad_u64_u32 v[8:9], s[4:5], s12, v5, 0
	v_add3_u32 v9, v9, v10, v11
	v_lshl_add_u64 v[8:9], v[8:9], 1, v[6:7]
	s_waitcnt lgkmcnt(0)
	global_store_dwordx4 v[8:9], v[0:3], off
	s_movk_i32 s98, 0xffc0
	s_cmp_eq_u32 s99, 0
	s_cselect_b32 s98, 0x180, s98
	s_cmp_lt_i32 s27, s98
	s_nop 0
	v_add_u32_e32 v0, 0x400, v22
	v_ashrrev_i32_e32 v5, 5, v0
	v_mad_u64_u32 v[0:1], s[4:5], v5, s69, v[4:5]
	ds_read_b128 v[0:3], v0
	v_add_u32_e32 v5, v24, v5
	v_ashrrev_i32_e32 v8, 31, v5
	v_mul_lo_u32 v10, s12, v8
	v_mul_lo_u32 v11, s13, v5
	v_mad_u64_u32 v[8:9], s[4:5], s12, v5, 0
	v_add3_u32 v9, v9, v10, v11
	v_lshl_add_u64 v[8:9], v[8:9], 1, v[6:7]
	s_waitcnt lgkmcnt(0)
	global_store_dwordx4 v[8:9], v[0:3], off
	s_nop 1
	v_add_u32_e32 v0, 0x600, v22
	v_ashrrev_i32_e32 v5, 5, v0
	v_mad_u64_u32 v[0:1], s[4:5], v5, s69, v[4:5]
	ds_read_b128 v[0:3], v0
	v_add_u32_e32 v4, v24, v5
	v_ashrrev_i32_e32 v5, 31, v4
	v_mul_lo_u32 v8, s12, v5
	v_mul_lo_u32 v9, s13, v4
	v_mad_u64_u32 v[4:5], s[4:5], s12, v4, 0
	v_add3_u32 v5, v5, v8, v9
	v_lshl_add_u64 v[4:5], v[4:5], 1, v[6:7]
	s_waitcnt lgkmcnt(0)
	global_store_dwordx4 v[4:5], v[0:3], off
	s_barrier
	s_cbranch_scc0 .LBB0_1499
